# P0 RMSNorm rows rewritten by hand: gains loaded once, next row prefetched (2 register sets), DPP+readlane wave sum
# speedup vs baseline: 1.0145x; 1.0021x over previous
.LBB0_48:
	s_waitcnt lgkmcnt(0)
	s_add_u32 s16, s38, 0x6000000
	s_addc_u32 s17, s39, 0
	s_cmpk_gt_i32 s3, 0x47ff
	v_mbcnt_lo_u32_b32 v187, -1, 0
	s_cbranch_scc1 .LBB0_55
	v_mbcnt_hi_u32_b32 v100, -1, v187
	v_mov_b32_e32 v35, 0x358637bd
	s_mov_b32 s23, 0xf800000
	v_mov_b32_e32 v101, 0x260
	v_lshlrev_b32_e32 v100, 4, v100
	s_add_u32 s18, s12, 0x1000
	s_addc_u32 s19, s13, 0
	global_load_dwordx4 v[112:115], v100, s[18:19] offset:-4096
	global_load_dwordx4 v[116:119], v100, s[18:19] offset:-3072
	global_load_dwordx4 v[120:123], v100, s[18:19] offset:-2048
	global_load_dwordx4 v[124:127], v100, s[18:19] offset:-1024
	global_load_dwordx4 v[128:131], v100, s[18:19] offset:0
	global_load_dwordx4 v[132:135], v100, s[18:19] offset:1024
	global_load_dwordx4 v[136:139], v100, s[18:19] offset:2048
	global_load_dwordx4 v[140:143], v100, s[18:19] offset:3072
	s_add_u32 s18, s14, 0x1000
	s_addc_u32 s19, s15, 0
	global_load_dwordx4 v[188:191], v100, s[18:19] offset:-4096
	global_load_dwordx4 v[192:195], v100, s[18:19] offset:-3072
	global_load_dwordx4 v[196:199], v100, s[18:19] offset:-2048
	global_load_dwordx4 v[200:203], v100, s[18:19] offset:-1024
	global_load_dwordx4 v[204:207], v100, s[18:19] offset:0
	global_load_dwordx4 v[208:211], v100, s[18:19] offset:1024
	global_load_dwordx4 v[212:215], v100, s[18:19] offset:2048
	global_load_dwordx4 v[216:219], v100, s[18:19] offset:3072
	s_cmpk_lt_i32 s3, 0x4000
	s_cselect_b32 s18, s8, s10
	s_cselect_b32 s19, s9, s11
	s_cselect_b32 s20, 0, 0x4000
	s_sub_i32 s20, s3, s20
	s_lshl_b32 s20, s20, 13
	s_add_u32 s18, s18, s20
	s_addc_u32 s19, s19, 0
	s_add_u32 s18, s18, 0x1000
	s_addc_u32 s19, s19, 0
	global_load_dwordx4 v[2:5], v100, s[18:19] offset:-4096 nt
	global_load_dwordx4 v[6:9], v100, s[18:19] offset:-3072 nt
	global_load_dwordx4 v[10:13], v100, s[18:19] offset:-2048 nt
	global_load_dwordx4 v[14:17], v100, s[18:19] offset:-1024 nt
	global_load_dwordx4 v[18:21], v100, s[18:19] offset:0 nt
	global_load_dwordx4 v[22:25], v100, s[18:19] offset:1024 nt
	global_load_dwordx4 v[26:29], v100, s[18:19] offset:2048 nt
	global_load_dwordx4 v[30:33], v100, s[18:19] offset:3072 nt
	s_add_i32 s21, s3, s50
	s_cmpk_lt_i32 s21, 0x4800
	s_cbranch_scc0 .Lrms_nn_0
	s_cmpk_lt_i32 s21, 0x4000
	s_cselect_b32 s18, s8, s10
	s_cselect_b32 s19, s9, s11
	s_cselect_b32 s20, 0, 0x4000
	s_sub_i32 s20, s21, s20
	s_lshl_b32 s20, s20, 13
	s_add_u32 s18, s18, s20
	s_addc_u32 s19, s19, 0
	s_add_u32 s18, s18, 0x1000
	s_addc_u32 s19, s19, 0
	global_load_dwordx4 v[36:39], v100, s[18:19] offset:-4096 nt
	global_load_dwordx4 v[40:43], v100, s[18:19] offset:-3072 nt
	global_load_dwordx4 v[44:47], v100, s[18:19] offset:-2048 nt
	global_load_dwordx4 v[48:51], v100, s[18:19] offset:-1024 nt
	global_load_dwordx4 v[52:55], v100, s[18:19] offset:0 nt
	global_load_dwordx4 v[56:59], v100, s[18:19] offset:1024 nt
	global_load_dwordx4 v[60:63], v100, s[18:19] offset:2048 nt
	global_load_dwordx4 v[64:67], v100, s[18:19] offset:3072 nt
	s_waitcnt vmcnt(8)
	s_branch .Lrms_go_0

.Lrms_go_0:
	v_pk_mul_f32 v[68:69], v[2:3], v[2:3]
	v_pk_mul_f32 v[70:71], v[4:5], v[4:5]
	v_pk_fma_f32 v[68:69], v[6:7], v[6:7], v[68:69]
	v_pk_fma_f32 v[70:71], v[8:9], v[8:9], v[70:71]
	v_pk_fma_f32 v[68:69], v[10:11], v[10:11], v[68:69]
	v_pk_fma_f32 v[70:71], v[12:13], v[12:13], v[70:71]
	v_pk_fma_f32 v[68:69], v[14:15], v[14:15], v[68:69]
	v_pk_fma_f32 v[70:71], v[16:17], v[16:17], v[70:71]
	v_pk_fma_f32 v[68:69], v[18:19], v[18:19], v[68:69]
	v_pk_fma_f32 v[70:71], v[20:21], v[20:21], v[70:71]
	v_pk_fma_f32 v[68:69], v[22:23], v[22:23], v[68:69]
	v_pk_fma_f32 v[70:71], v[24:25], v[24:25], v[70:71]
	v_pk_fma_f32 v[68:69], v[26:27], v[26:27], v[68:69]
	v_pk_fma_f32 v[70:71], v[28:29], v[28:29], v[70:71]
	v_pk_fma_f32 v[68:69], v[30:31], v[30:31], v[68:69]
	v_pk_fma_f32 v[70:71], v[32:33], v[32:33], v[70:71]
	v_pk_add_f32 v[68:69], v[68:69], v[70:71]
	s_mul_i32 s12, s3, 0x1400
	v_add_f32_e32 v78, v68, v69
	s_add_u32 s12, s16, s12
	s_addc_u32 s13, s17, 0
	s_nop 1
	v_add_f32_dpp v78, v78, v78 quad_perm:[1,0,3,2] row_mask:0xf bank_mask:0xf
	s_nop 1
	v_add_f32_dpp v78, v78, v78 quad_perm:[2,3,0,1] row_mask:0xf bank_mask:0xf
	s_nop 1
	v_add_f32_dpp v78, v78, v78 row_half_mirror row_mask:0xf bank_mask:0xf
	s_nop 1
	v_add_f32_dpp v78, v78, v78 row_mirror row_mask:0xf bank_mask:0xf
	s_nop 1
	v_readlane_b32 s6, v78, 0
	v_readlane_b32 s7, v78, 16
	v_readlane_b32 s20, v78, 32
	v_readlane_b32 s22, v78, 48
	v_mov_b32_e32 v78, s6
	v_add_f32_e32 v78, s7, v78
	v_add_f32_e32 v78, s20, v78
	v_add_f32_e32 v78, s22, v78
	v_fmamk_f32 v78, v78, 0x3a000000, v35
	v_mul_f32_e32 v79, 0x4f800000, v78
	v_cmp_gt_f32_e32 vcc, s23, v78
	s_nop 1
	v_cndmask_b32_e32 v78, v78, v79, vcc
	v_sqrt_f32_e32 v79, v78
	s_nop 0
	v_add_u32_e32 v80, -1, v79
	v_add_u32_e32 v81, 1, v79
	v_fma_f32 v82, -v80, v79, v78
	v_fma_f32 v83, -v81, v79, v78
	v_cmp_ge_f32_e64 s[6:7], 0, v82
	s_nop 1
	v_cndmask_b32_e64 v79, v79, v80, s[6:7]
	v_cmp_lt_f32_e64 s[6:7], 0, v83
	s_nop 1
	v_cndmask_b32_e64 v79, v79, v81, s[6:7]
	v_mul_f32_e32 v80, 0x37800000, v79
	v_cndmask_b32_e32 v79, v79, v80, vcc
	v_cmp_class_f32_e32 vcc, v78, v101
	s_nop 1
	v_cndmask_b32_e32 v80, v79, v78, vcc
	v_div_scale_f32 v81, s[6:7], v80, v80, 1.0
	v_rcp_f32_e32 v82, v81
	v_div_scale_f32 v83, vcc, 1.0, v80, 1.0
	s_nop 0
	v_fma_f32 v84, -v81, v82, 1.0
	v_fmac_f32_e32 v82, v84, v82
	v_mul_f32_e32 v84, v83, v82
	v_fma_f32 v85, -v81, v84, v83
	v_fmac_f32_e32 v84, v85, v82
	v_fma_f32 v81, -v81, v84, v83
	v_div_fmas_f32 v81, v81, v82, v84
	v_div_fixup_f32 v80, v81, v80, 1.0
	s_cmpk_lt_i32 s3, 0x4000
	s_cbranch_scc0 .Lrms_gm_0
	v_pk_mul_f32 v[2:3], v[2:3], v[80:81] op_sel_hi:[1,0]
	v_pk_mul_f32 v[4:5], v[4:5], v[80:81] op_sel_hi:[1,0]
	v_pk_mul_f32 v[6:7], v[6:7], v[80:81] op_sel_hi:[1,0]
	v_pk_mul_f32 v[8:9], v[8:9], v[80:81] op_sel_hi:[1,0]
	v_pk_mul_f32 v[10:11], v[10:11], v[80:81] op_sel_hi:[1,0]
	v_pk_mul_f32 v[12:13], v[12:13], v[80:81] op_sel_hi:[1,0]
	v_pk_mul_f32 v[14:15], v[14:15], v[80:81] op_sel_hi:[1,0]
	v_pk_mul_f32 v[16:17], v[16:17], v[80:81] op_sel_hi:[1,0]
	v_pk_mul_f32 v[18:19], v[18:19], v[80:81] op_sel_hi:[1,0]
	v_pk_mul_f32 v[20:21], v[20:21], v[80:81] op_sel_hi:[1,0]
	v_pk_mul_f32 v[22:23], v[22:23], v[80:81] op_sel_hi:[1,0]
	v_pk_mul_f32 v[24:25], v[24:25], v[80:81] op_sel_hi:[1,0]
	v_pk_mul_f32 v[26:27], v[26:27], v[80:81] op_sel_hi:[1,0]
	v_pk_mul_f32 v[28:29], v[28:29], v[80:81] op_sel_hi:[1,0]
	v_pk_mul_f32 v[30:31], v[30:31], v[80:81] op_sel_hi:[1,0]
	v_pk_mul_f32 v[32:33], v[32:33], v[80:81] op_sel_hi:[1,0]
	v_pk_mul_f32 v[2:3], v[112:113], v[2:3]
	v_pk_mul_f32 v[4:5], v[114:115], v[4:5]
	v_cvt_pk_bf16_f32 v2, v2, v3
	v_cvt_pk_bf16_f32 v3, v4, v5
	global_store_dwordx2 v34, v[2:3], s[12:13] offset:0
	v_pk_mul_f32 v[6:7], v[116:117], v[6:7]
	v_pk_mul_f32 v[8:9], v[118:119], v[8:9]
	v_cvt_pk_bf16_f32 v6, v6, v7
	v_cvt_pk_bf16_f32 v7, v8, v9
	global_store_dwordx2 v34, v[6:7], s[12:13] offset:512
	v_pk_mul_f32 v[10:11], v[120:121], v[10:11]
	v_pk_mul_f32 v[12:13], v[122:123], v[12:13]
	v_cvt_pk_bf16_f32 v10, v10, v11
	v_cvt_pk_bf16_f32 v11, v12, v13
	global_store_dwordx2 v34, v[10:11], s[12:13] offset:1024
	v_pk_mul_f32 v[14:15], v[124:125], v[14:15]
	v_pk_mul_f32 v[16:17], v[126:127], v[16:17]
	v_cvt_pk_bf16_f32 v14, v14, v15
	v_cvt_pk_bf16_f32 v15, v16, v17
	global_store_dwordx2 v34, v[14:15], s[12:13] offset:1536
	v_pk_mul_f32 v[18:19], v[128:129], v[18:19]
	v_pk_mul_f32 v[20:21], v[130:131], v[20:21]
	v_cvt_pk_bf16_f32 v18, v18, v19
	v_cvt_pk_bf16_f32 v19, v20, v21
	global_store_dwordx2 v34, v[18:19], s[12:13] offset:2048
	v_pk_mul_f32 v[22:23], v[132:133], v[22:23]
	v_pk_mul_f32 v[24:25], v[134:135], v[24:25]
	v_cvt_pk_bf16_f32 v22, v22, v23
	v_cvt_pk_bf16_f32 v23, v24, v25
	global_store_dwordx2 v34, v[22:23], s[12:13] offset:2560
	v_pk_mul_f32 v[26:27], v[136:137], v[26:27]
	v_pk_mul_f32 v[28:29], v[138:139], v[28:29]
	v_cvt_pk_bf16_f32 v26, v26, v27
	v_cvt_pk_bf16_f32 v27, v28, v29
	global_store_dwordx2 v34, v[26:27], s[12:13] offset:3072
	v_pk_mul_f32 v[30:31], v[140:141], v[30:31]
	v_pk_mul_f32 v[32:33], v[142:143], v[32:33]
	v_cvt_pk_bf16_f32 v30, v30, v31
	v_cvt_pk_bf16_f32 v31, v32, v33
	global_store_dwordx2 v34, v[30:31], s[12:13] offset:3584
	s_branch .Lrms_jn_0
.Lrms_gm_0:
	v_pk_mul_f32 v[2:3], v[2:3], v[80:81] op_sel_hi:[1,0]
	v_pk_mul_f32 v[4:5], v[4:5], v[80:81] op_sel_hi:[1,0]
	v_pk_mul_f32 v[6:7], v[6:7], v[80:81] op_sel_hi:[1,0]
	v_pk_mul_f32 v[8:9], v[8:9], v[80:81] op_sel_hi:[1,0]
	v_pk_mul_f32 v[10:11], v[10:11], v[80:81] op_sel_hi:[1,0]
	v_pk_mul_f32 v[12:13], v[12:13], v[80:81] op_sel_hi:[1,0]
	v_pk_mul_f32 v[14:15], v[14:15], v[80:81] op_sel_hi:[1,0]
	v_pk_mul_f32 v[16:17], v[16:17], v[80:81] op_sel_hi:[1,0]
	v_pk_mul_f32 v[18:19], v[18:19], v[80:81] op_sel_hi:[1,0]
	v_pk_mul_f32 v[20:21], v[20:21], v[80:81] op_sel_hi:[1,0]
	v_pk_mul_f32 v[22:23], v[22:23], v[80:81] op_sel_hi:[1,0]
	v_pk_mul_f32 v[24:25], v[24:25], v[80:81] op_sel_hi:[1,0]
	v_pk_mul_f32 v[26:27], v[26:27], v[80:81] op_sel_hi:[1,0]
	v_pk_mul_f32 v[28:29], v[28:29], v[80:81] op_sel_hi:[1,0]
	v_pk_mul_f32 v[30:31], v[30:31], v[80:81] op_sel_hi:[1,0]
	v_pk_mul_f32 v[32:33], v[32:33], v[80:81] op_sel_hi:[1,0]
	v_pk_mul_f32 v[2:3], v[188:189], v[2:3]
	v_pk_mul_f32 v[4:5], v[190:191], v[4:5]
	v_cvt_pk_bf16_f32 v2, v2, v3
	v_cvt_pk_bf16_f32 v3, v4, v5
	global_store_dwordx2 v34, v[2:3], s[12:13] offset:0
	v_pk_mul_f32 v[6:7], v[192:193], v[6:7]
	v_pk_mul_f32 v[8:9], v[194:195], v[8:9]
	v_cvt_pk_bf16_f32 v6, v6, v7
	v_cvt_pk_bf16_f32 v7, v8, v9
	global_store_dwordx2 v34, v[6:7], s[12:13] offset:512
	v_pk_mul_f32 v[10:11], v[196:197], v[10:11]
	v_pk_mul_f32 v[12:13], v[198:199], v[12:13]
	v_cvt_pk_bf16_f32 v10, v10, v11
	v_cvt_pk_bf16_f32 v11, v12, v13
	global_store_dwordx2 v34, v[10:11], s[12:13] offset:1024
	v_pk_mul_f32 v[14:15], v[200:201], v[14:15]
	v_pk_mul_f32 v[16:17], v[202:203], v[16:17]
	v_cvt_pk_bf16_f32 v14, v14, v15
	v_cvt_pk_bf16_f32 v15, v16, v17
	global_store_dwordx2 v34, v[14:15], s[12:13] offset:1536
	v_pk_mul_f32 v[18:19], v[204:205], v[18:19]
	v_pk_mul_f32 v[20:21], v[206:207], v[20:21]
	v_cvt_pk_bf16_f32 v18, v18, v19
	v_cvt_pk_bf16_f32 v19, v20, v21
	global_store_dwordx2 v34, v[18:19], s[12:13] offset:2048
	v_pk_mul_f32 v[22:23], v[208:209], v[22:23]
	v_pk_mul_f32 v[24:25], v[210:211], v[24:25]
	v_cvt_pk_bf16_f32 v22, v22, v23
	v_cvt_pk_bf16_f32 v23, v24, v25
	global_store_dwordx2 v34, v[22:23], s[12:13] offset:2560
	v_pk_mul_f32 v[26:27], v[212:213], v[26:27]
	v_pk_mul_f32 v[28:29], v[214:215], v[28:29]
	v_cvt_pk_bf16_f32 v26, v26, v27
	v_cvt_pk_bf16_f32 v27, v28, v29
	global_store_dwordx2 v34, v[26:27], s[12:13] offset:3072
	v_pk_mul_f32 v[30:31], v[216:217], v[30:31]
	v_pk_mul_f32 v[32:33], v[218:219], v[32:33]
	v_cvt_pk_bf16_f32 v30, v30, v31
	v_cvt_pk_bf16_f32 v31, v32, v33
	global_store_dwordx2 v34, v[30:31], s[12:13] offset:3584
.Lrms_jn_0:
	s_mov_b32 s3, s21
	s_cmpk_lt_i32 s3, 0x4800
	s_cbranch_scc0 .LBB0_55
.Lrms_loop:
	s_add_i32 s21, s3, s50
	s_cmpk_lt_i32 s21, 0x4800
	s_cbranch_scc0 .Lrms_nn_1
	s_cmpk_lt_i32 s21, 0x4000
	s_cselect_b32 s18, s8, s10
	s_cselect_b32 s19, s9, s11
	s_cselect_b32 s20, 0, 0x4000
	s_sub_i32 s20, s21, s20
	s_lshl_b32 s20, s20, 13
	s_add_u32 s18, s18, s20
	s_addc_u32 s19, s19, 0
	s_add_u32 s18, s18, 0x1000
	s_addc_u32 s19, s19, 0
	global_load_dwordx4 v[2:5], v100, s[18:19] offset:-4096 nt
	global_load_dwordx4 v[6:9], v100, s[18:19] offset:-3072 nt
	global_load_dwordx4 v[10:13], v100, s[18:19] offset:-2048 nt
	global_load_dwordx4 v[14:17], v100, s[18:19] offset:-1024 nt
	global_load_dwordx4 v[18:21], v100, s[18:19] offset:0 nt
	global_load_dwordx4 v[22:25], v100, s[18:19] offset:1024 nt
	global_load_dwordx4 v[26:29], v100, s[18:19] offset:2048 nt
	global_load_dwordx4 v[30:33], v100, s[18:19] offset:3072 nt
	s_waitcnt vmcnt(16)
	s_branch .Lrms_go_1

.Lrms_go_1:
	v_pk_mul_f32 v[68:69], v[36:37], v[36:37]
	v_pk_mul_f32 v[70:71], v[38:39], v[38:39]
	v_pk_fma_f32 v[68:69], v[40:41], v[40:41], v[68:69]
	v_pk_fma_f32 v[70:71], v[42:43], v[42:43], v[70:71]
	v_pk_fma_f32 v[68:69], v[44:45], v[44:45], v[68:69]
	v_pk_fma_f32 v[70:71], v[46:47], v[46:47], v[70:71]
	v_pk_fma_f32 v[68:69], v[48:49], v[48:49], v[68:69]
	v_pk_fma_f32 v[70:71], v[50:51], v[50:51], v[70:71]
	v_pk_fma_f32 v[68:69], v[52:53], v[52:53], v[68:69]
	v_pk_fma_f32 v[70:71], v[54:55], v[54:55], v[70:71]
	v_pk_fma_f32 v[68:69], v[56:57], v[56:57], v[68:69]
	v_pk_fma_f32 v[70:71], v[58:59], v[58:59], v[70:71]
	v_pk_fma_f32 v[68:69], v[60:61], v[60:61], v[68:69]
	v_pk_fma_f32 v[70:71], v[62:63], v[62:63], v[70:71]
	v_pk_fma_f32 v[68:69], v[64:65], v[64:65], v[68:69]
	v_pk_fma_f32 v[70:71], v[66:67], v[66:67], v[70:71]
	v_pk_add_f32 v[68:69], v[68:69], v[70:71]
	s_mul_i32 s12, s3, 0x1400
	v_add_f32_e32 v78, v68, v69
	s_add_u32 s12, s16, s12
	s_addc_u32 s13, s17, 0
	s_nop 1
	v_add_f32_dpp v78, v78, v78 quad_perm:[1,0,3,2] row_mask:0xf bank_mask:0xf
	s_nop 1
	v_add_f32_dpp v78, v78, v78 quad_perm:[2,3,0,1] row_mask:0xf bank_mask:0xf
	s_nop 1
	v_add_f32_dpp v78, v78, v78 row_half_mirror row_mask:0xf bank_mask:0xf
	s_nop 1
	v_add_f32_dpp v78, v78, v78 row_mirror row_mask:0xf bank_mask:0xf
	s_nop 1
	v_readlane_b32 s6, v78, 0
	v_readlane_b32 s7, v78, 16
	v_readlane_b32 s20, v78, 32
	v_readlane_b32 s22, v78, 48
	v_mov_b32_e32 v78, s6
	v_add_f32_e32 v78, s7, v78
	v_add_f32_e32 v78, s20, v78
	v_add_f32_e32 v78, s22, v78
	v_fmamk_f32 v78, v78, 0x3a000000, v35
	v_mul_f32_e32 v79, 0x4f800000, v78
	v_cmp_gt_f32_e32 vcc, s23, v78
	s_nop 1
	v_cndmask_b32_e32 v78, v78, v79, vcc
	v_sqrt_f32_e32 v79, v78
	s_nop 0
	v_add_u32_e32 v80, -1, v79
	v_add_u32_e32 v81, 1, v79
	v_fma_f32 v82, -v80, v79, v78
	v_fma_f32 v83, -v81, v79, v78
	v_cmp_ge_f32_e64 s[6:7], 0, v82
	s_nop 1
	v_cndmask_b32_e64 v79, v79, v80, s[6:7]
	v_cmp_lt_f32_e64 s[6:7], 0, v83
	s_nop 1
	v_cndmask_b32_e64 v79, v79, v81, s[6:7]
	v_mul_f32_e32 v80, 0x37800000, v79
	v_cndmask_b32_e32 v79, v79, v80, vcc
	v_cmp_class_f32_e32 vcc, v78, v101
	s_nop 1
	v_cndmask_b32_e32 v80, v79, v78, vcc
	v_div_scale_f32 v81, s[6:7], v80, v80, 1.0
	v_rcp_f32_e32 v82, v81
	v_div_scale_f32 v83, vcc, 1.0, v80, 1.0
	s_nop 0
	v_fma_f32 v84, -v81, v82, 1.0
	v_fmac_f32_e32 v82, v84, v82
	v_mul_f32_e32 v84, v83, v82
	v_fma_f32 v85, -v81, v84, v83
	v_fmac_f32_e32 v84, v85, v82
	v_fma_f32 v81, -v81, v84, v83
	v_div_fmas_f32 v81, v81, v82, v84
	v_div_fixup_f32 v80, v81, v80, 1.0
	s_cmpk_lt_i32 s3, 0x4000
	s_cbranch_scc0 .Lrms_gm_1
	v_pk_mul_f32 v[36:37], v[36:37], v[80:81] op_sel_hi:[1,0]
	v_pk_mul_f32 v[38:39], v[38:39], v[80:81] op_sel_hi:[1,0]
	v_pk_mul_f32 v[40:41], v[40:41], v[80:81] op_sel_hi:[1,0]
	v_pk_mul_f32 v[42:43], v[42:43], v[80:81] op_sel_hi:[1,0]
	v_pk_mul_f32 v[44:45], v[44:45], v[80:81] op_sel_hi:[1,0]
	v_pk_mul_f32 v[46:47], v[46:47], v[80:81] op_sel_hi:[1,0]
	v_pk_mul_f32 v[48:49], v[48:49], v[80:81] op_sel_hi:[1,0]
	v_pk_mul_f32 v[50:51], v[50:51], v[80:81] op_sel_hi:[1,0]
	v_pk_mul_f32 v[52:53], v[52:53], v[80:81] op_sel_hi:[1,0]
	v_pk_mul_f32 v[54:55], v[54:55], v[80:81] op_sel_hi:[1,0]
	v_pk_mul_f32 v[56:57], v[56:57], v[80:81] op_sel_hi:[1,0]
	v_pk_mul_f32 v[58:59], v[58:59], v[80:81] op_sel_hi:[1,0]
	v_pk_mul_f32 v[60:61], v[60:61], v[80:81] op_sel_hi:[1,0]
	v_pk_mul_f32 v[62:63], v[62:63], v[80:81] op_sel_hi:[1,0]
	v_pk_mul_f32 v[64:65], v[64:65], v[80:81] op_sel_hi:[1,0]
	v_pk_mul_f32 v[66:67], v[66:67], v[80:81] op_sel_hi:[1,0]
	v_pk_mul_f32 v[36:37], v[112:113], v[36:37]
	v_pk_mul_f32 v[38:39], v[114:115], v[38:39]
	v_cvt_pk_bf16_f32 v36, v36, v37
	v_cvt_pk_bf16_f32 v37, v38, v39
	global_store_dwordx2 v34, v[36:37], s[12:13] offset:0
	v_pk_mul_f32 v[40:41], v[116:117], v[40:41]
	v_pk_mul_f32 v[42:43], v[118:119], v[42:43]
	v_cvt_pk_bf16_f32 v40, v40, v41
	v_cvt_pk_bf16_f32 v41, v42, v43
	global_store_dwordx2 v34, v[40:41], s[12:13] offset:512
	v_pk_mul_f32 v[44:45], v[120:121], v[44:45]
	v_pk_mul_f32 v[46:47], v[122:123], v[46:47]
	v_cvt_pk_bf16_f32 v44, v44, v45
	v_cvt_pk_bf16_f32 v45, v46, v47
	global_store_dwordx2 v34, v[44:45], s[12:13] offset:1024
	v_pk_mul_f32 v[48:49], v[124:125], v[48:49]
	v_pk_mul_f32 v[50:51], v[126:127], v[50:51]
	v_cvt_pk_bf16_f32 v48, v48, v49
	v_cvt_pk_bf16_f32 v49, v50, v51
	global_store_dwordx2 v34, v[48:49], s[12:13] offset:1536
	v_pk_mul_f32 v[52:53], v[128:129], v[52:53]
	v_pk_mul_f32 v[54:55], v[130:131], v[54:55]
	v_cvt_pk_bf16_f32 v52, v52, v53
	v_cvt_pk_bf16_f32 v53, v54, v55
	global_store_dwordx2 v34, v[52:53], s[12:13] offset:2048
	v_pk_mul_f32 v[56:57], v[132:133], v[56:57]
	v_pk_mul_f32 v[58:59], v[134:135], v[58:59]
	v_cvt_pk_bf16_f32 v56, v56, v57
	v_cvt_pk_bf16_f32 v57, v58, v59
	global_store_dwordx2 v34, v[56:57], s[12:13] offset:2560
	v_pk_mul_f32 v[60:61], v[136:137], v[60:61]
	v_pk_mul_f32 v[62:63], v[138:139], v[62:63]
	v_cvt_pk_bf16_f32 v60, v60, v61
	v_cvt_pk_bf16_f32 v61, v62, v63
	global_store_dwordx2 v34, v[60:61], s[12:13] offset:3072
	v_pk_mul_f32 v[64:65], v[140:141], v[64:65]
	v_pk_mul_f32 v[66:67], v[142:143], v[66:67]
	v_cvt_pk_bf16_f32 v64, v64, v65
	v_cvt_pk_bf16_f32 v65, v66, v67
	global_store_dwordx2 v34, v[64:65], s[12:13] offset:3584
	s_branch .Lrms_jn_1
.Lrms_gm_1:
	v_pk_mul_f32 v[36:37], v[36:37], v[80:81] op_sel_hi:[1,0]
	v_pk_mul_f32 v[38:39], v[38:39], v[80:81] op_sel_hi:[1,0]
	v_pk_mul_f32 v[40:41], v[40:41], v[80:81] op_sel_hi:[1,0]
	v_pk_mul_f32 v[42:43], v[42:43], v[80:81] op_sel_hi:[1,0]
	v_pk_mul_f32 v[44:45], v[44:45], v[80:81] op_sel_hi:[1,0]
	v_pk_mul_f32 v[46:47], v[46:47], v[80:81] op_sel_hi:[1,0]
	v_pk_mul_f32 v[48:49], v[48:49], v[80:81] op_sel_hi:[1,0]
	v_pk_mul_f32 v[50:51], v[50:51], v[80:81] op_sel_hi:[1,0]
	v_pk_mul_f32 v[52:53], v[52:53], v[80:81] op_sel_hi:[1,0]
	v_pk_mul_f32 v[54:55], v[54:55], v[80:81] op_sel_hi:[1,0]
	v_pk_mul_f32 v[56:57], v[56:57], v[80:81] op_sel_hi:[1,0]
	v_pk_mul_f32 v[58:59], v[58:59], v[80:81] op_sel_hi:[1,0]
	v_pk_mul_f32 v[60:61], v[60:61], v[80:81] op_sel_hi:[1,0]
	v_pk_mul_f32 v[62:63], v[62:63], v[80:81] op_sel_hi:[1,0]
	v_pk_mul_f32 v[64:65], v[64:65], v[80:81] op_sel_hi:[1,0]
	v_pk_mul_f32 v[66:67], v[66:67], v[80:81] op_sel_hi:[1,0]
	v_pk_mul_f32 v[36:37], v[188:189], v[36:37]
	v_pk_mul_f32 v[38:39], v[190:191], v[38:39]
	v_cvt_pk_bf16_f32 v36, v36, v37
	v_cvt_pk_bf16_f32 v37, v38, v39
	global_store_dwordx2 v34, v[36:37], s[12:13] offset:0
	v_pk_mul_f32 v[40:41], v[192:193], v[40:41]
	v_pk_mul_f32 v[42:43], v[194:195], v[42:43]
	v_cvt_pk_bf16_f32 v40, v40, v41
	v_cvt_pk_bf16_f32 v41, v42, v43
	global_store_dwordx2 v34, v[40:41], s[12:13] offset:512
	v_pk_mul_f32 v[44:45], v[196:197], v[44:45]
	v_pk_mul_f32 v[46:47], v[198:199], v[46:47]
	v_cvt_pk_bf16_f32 v44, v44, v45
	v_cvt_pk_bf16_f32 v45, v46, v47
	global_store_dwordx2 v34, v[44:45], s[12:13] offset:1024
	v_pk_mul_f32 v[48:49], v[200:201], v[48:49]
	v_pk_mul_f32 v[50:51], v[202:203], v[50:51]
	v_cvt_pk_bf16_f32 v48, v48, v49
	v_cvt_pk_bf16_f32 v49, v50, v51
	global_store_dwordx2 v34, v[48:49], s[12:13] offset:1536
	v_pk_mul_f32 v[52:53], v[204:205], v[52:53]
	v_pk_mul_f32 v[54:55], v[206:207], v[54:55]
	v_cvt_pk_bf16_f32 v52, v52, v53
	v_cvt_pk_bf16_f32 v53, v54, v55
	global_store_dwordx2 v34, v[52:53], s[12:13] offset:2048
	v_pk_mul_f32 v[56:57], v[208:209], v[56:57]
	v_pk_mul_f32 v[58:59], v[210:211], v[58:59]
	v_cvt_pk_bf16_f32 v56, v56, v57
	v_cvt_pk_bf16_f32 v57, v58, v59
	global_store_dwordx2 v34, v[56:57], s[12:13] offset:2560
	v_pk_mul_f32 v[60:61], v[212:213], v[60:61]
	v_pk_mul_f32 v[62:63], v[214:215], v[62:63]
	v_cvt_pk_bf16_f32 v60, v60, v61
	v_cvt_pk_bf16_f32 v61, v62, v63
	global_store_dwordx2 v34, v[60:61], s[12:13] offset:3072
	v_pk_mul_f32 v[64:65], v[216:217], v[64:65]
	v_pk_mul_f32 v[66:67], v[218:219], v[66:67]
	v_cvt_pk_bf16_f32 v64, v64, v65
	v_cvt_pk_bf16_f32 v65, v66, v67
	global_store_dwordx2 v34, v[64:65], s[12:13] offset:3584
.Lrms_jn_1:
	s_mov_b32 s3, s21
	s_cmpk_lt_i32 s3, 0x4800
	s_cbranch_scc0 .LBB0_55
	s_add_i32 s21, s3, s50
	s_cmpk_lt_i32 s21, 0x4800
	s_cbranch_scc0 .Lrms_nn_2
	s_cmpk_lt_i32 s21, 0x4000
	s_cselect_b32 s18, s8, s10
	s_cselect_b32 s19, s9, s11
	s_cselect_b32 s20, 0, 0x4000
	s_sub_i32 s20, s21, s20
	s_lshl_b32 s20, s20, 13
	s_add_u32 s18, s18, s20
	s_addc_u32 s19, s19, 0
	s_add_u32 s18, s18, 0x1000
	s_addc_u32 s19, s19, 0
	global_load_dwordx4 v[36:39], v100, s[18:19] offset:-4096 nt
	global_load_dwordx4 v[40:43], v100, s[18:19] offset:-3072 nt
	global_load_dwordx4 v[44:47], v100, s[18:19] offset:-2048 nt
	global_load_dwordx4 v[48:51], v100, s[18:19] offset:-1024 nt
	global_load_dwordx4 v[52:55], v100, s[18:19] offset:0 nt
	global_load_dwordx4 v[56:59], v100, s[18:19] offset:1024 nt
	global_load_dwordx4 v[60:63], v100, s[18:19] offset:2048 nt
	global_load_dwordx4 v[64:67], v100, s[18:19] offset:3072 nt
	s_waitcnt vmcnt(16)
	s_branch .Lrms_go_2

.Lrms_jn_2:
	s_mov_b32 s3, s21
	s_cmpk_lt_i32 s3, 0x4800
	s_cbranch_scc1 .Lrms_loop
